# best_v12 + layer-0 gemmU gate-fold loads issued together + layer-0 post LoRA operand loads de-serialised
# baseline (speedup 1.0000x reference)
.LBB0_536:
	s_or_b64 exec, exec, s[10:11]
	s_waitcnt vmcnt(0)
	v_cvt_f32_f16_e32 v8, v0
	v_cvt_f32_f16_sdwa v18, v0 dst_sel:DWORD dst_unused:UNUSED_PAD src0_sel:WORD_1
	s_mov_b32 s88, 0
	s_mov_b64 s[12:13], -1
	v_sub_f32_e32 v12, v12, v8
	global_load_dwordx4 v[8:11], v[26:27], off offset:3600
	global_load_dwordx4 v[48:51], v[26:27], off offset:3584
	v_sub_f32_e32 v13, v13, v18
	v_add_u32_e32 v18, 0x2000, v85
	s_waitcnt vmcnt(0)
	v_fma_mix_f32 v12, v12, v48, v0 op_sel_hi:[0,0,1]
	v_fma_mix_f32 v0, v13, v49, v0 op_sel:[0,0,1] op_sel_hi:[0,0,1]
	v_cvt_f32_f16_e32 v13, v1
	v_mul_f32_e32 v12, 0xbfb8aa3b, v12
	v_mul_f32_e32 v0, 0xbfb8aa3b, v0
	v_exp_f32_e32 v12, v12
	v_sub_f32_e32 v13, v14, v13
	v_cvt_f32_f16_sdwa v14, v1 dst_sel:DWORD dst_unused:UNUSED_PAD src0_sel:WORD_1
	v_fma_mix_f32 v13, v13, v50, v1 op_sel_hi:[0,0,1]
	v_mul_f32_e32 v13, 0xbfb8aa3b, v13
	v_exp_f32_e32 v0, v0
	v_sub_f32_e32 v14, v15, v14
	v_fma_mix_f32 v1, v14, v51, v1 op_sel:[0,0,1] op_sel_hi:[0,0,1]
	v_cvt_f32_f16_e32 v14, v2
	v_mul_f32_e32 v1, 0xbfb8aa3b, v1
	v_exp_f32_e32 v13, v13
	v_exp_f32_e32 v1, v1
	v_sub_f32_e32 v4, v4, v14
	v_fma_mix_f32 v4, v4, v8, v2 op_sel_hi:[0,0,1]
	v_cvt_f32_f16_sdwa v8, v2 dst_sel:DWORD dst_unused:UNUSED_PAD src0_sel:WORD_1
	v_mul_f32_e32 v4, 0xbfb8aa3b, v4
	v_exp_f32_e32 v4, v4
	v_add_f32_e32 v12, 1.0, v12
	v_sub_f32_e32 v5, v5, v8
	v_fma_mix_f32 v2, v5, v9, v2 op_sel:[0,0,1] op_sel_hi:[0,0,1]
	v_cvt_f32_f16_e32 v5, v3
	v_mul_f32_e32 v2, 0xbfb8aa3b, v2
	v_exp_f32_e32 v2, v2
	v_add_f32_e32 v0, 1.0, v0
	v_sub_f32_e32 v5, v6, v5
	v_cvt_f32_f16_sdwa v6, v3 dst_sel:DWORD dst_unused:UNUSED_PAD src0_sel:WORD_1
	v_fma_mix_f32 v5, v5, v10, v3 op_sel_hi:[0,0,1]
	v_mul_f32_e32 v5, 0xbfb8aa3b, v5
	v_exp_f32_e32 v5, v5
	v_sub_f32_e32 v6, v7, v6
	v_fma_mix_f32 v3, v6, v11, v3 op_sel:[0,0,1] op_sel_hi:[0,0,1]
	v_mul_f32_e32 v3, 0xbfb8aa3b, v3
	v_exp_f32_e32 v3, v3
	v_add_f32_e32 v13, 1.0, v13
	v_add_f32_e32 v1, 1.0, v1
	v_add_f32_e32 v4, 1.0, v4
	v_add_f32_e32 v2, 1.0, v2
	v_add_f32_e32 v5, 1.0, v5
	v_add_f32_e32 v3, 1.0, v3
	v_rcp_f32_e32 v12, v12
	v_rcp_f32_e32 v0, v0
	v_rcp_f32_e32 v13, v13
	v_rcp_f32_e32 v1, v1
	v_rcp_f32_e32 v4, v4
	v_rcp_f32_e32 v2, v2
	v_rcp_f32_e32 v5, v5
	v_rcp_f32_e32 v3, v3
	v_cvt_pk_f16_f32 v1, v13, v1
	v_cvt_pk_f16_f32 v2, v4, v2
	v_cvt_pk_f16_f32 v0, v12, v0
	v_cvt_pk_f16_f32 v3, v5, v3
	ds_write_b128 v80, v[0:3]
	s_waitcnt lgkmcnt(0)
	s_barrier
	ds_read_b128 v[4:7], v81
	ds_read_b128 v[8:11], v81 offset:64
	ds_read_b128 v[12:15], v81 offset:128
	ds_read_b128 v[0:3], v81 offset:192
	global_load_dwordx4 v[206:209], v[30:31], off
	global_load_dwordx4 v[210:213], v[30:31], off offset:64
	global_load_dwordx4 v[214:217], v[30:31], off offset:128
	global_load_dwordx4 v[218:221], v[30:31], off offset:192
	global_load_dwordx4 v[222:225], v[32:33], off
	global_load_dwordx4 v[226:229], v[32:33], off offset:64
	global_load_dwordx4 v[230:233], v[32:33], off offset:128
	global_load_dwordx4 v[234:237], v[32:33], off offset:192
	global_load_dwordx4 v[238:241], v[34:35], off
	global_load_dwordx4 v[242:245], v[34:35], off offset:64
	global_load_dwordx4 v[246:249], v[34:35], off offset:128
	global_load_dwordx4 v[250:253], v[34:35], off offset:192
	s_waitcnt vmcnt(11) lgkmcnt(3)
	v_mfma_f32_16x16x32_f16 v[48:51], v[4:7], v[206:209], 0
	s_waitcnt vmcnt(10) lgkmcnt(2)
	v_mfma_f32_16x16x32_f16 v[48:51], v[8:11], v[210:213], v[48:51]
	s_waitcnt vmcnt(9) lgkmcnt(1)
	v_mfma_f32_16x16x32_f16 v[48:51], v[12:15], v[214:217], v[48:51]
	s_waitcnt vmcnt(8) lgkmcnt(0)
	v_mfma_f32_16x16x32_f16 v[48:51], v[0:3], v[218:221], v[48:51]
	s_waitcnt vmcnt(7)
	v_mfma_f32_16x16x32_f16 v[52:55], v[4:7], v[222:225], 0
	s_waitcnt vmcnt(6)
	v_mfma_f32_16x16x32_f16 v[52:55], v[8:11], v[226:229], v[52:55]
	s_waitcnt vmcnt(5)
	v_mfma_f32_16x16x32_f16 v[52:55], v[12:15], v[230:233], v[52:55]
	s_waitcnt vmcnt(4)
	v_mfma_f32_16x16x32_f16 v[52:55], v[0:3], v[234:237], v[52:55]
	global_load_dwordx4 v[206:209], v[36:37], off
	global_load_dwordx4 v[210:213], v[36:37], off offset:64
	global_load_dwordx4 v[214:217], v[36:37], off offset:128
	global_load_dwordx4 v[218:221], v[36:37], off offset:192
	v_add_u32_e32 v56, 0x2400, v85
	v_add_u32_e32 v57, 0x2800, v85
	v_add_u32_e32 v58, 0x2c00, v85
	s_nop 4
	ds_write2_b32 v18, v48, v52 offset1:16
	ds_write2_b32 v56, v49, v53 offset1:16
	ds_write2_b32 v57, v50, v54 offset1:16
	ds_write2_b32 v58, v51, v55 offset1:16
	s_nop 3
	s_waitcnt vmcnt(7)
	v_mfma_f32_16x16x32_f16 v[48:51], v[4:7], v[238:241], 0
	s_waitcnt vmcnt(6)
	v_mfma_f32_16x16x32_f16 v[48:51], v[8:11], v[242:245], v[48:51]
	s_waitcnt vmcnt(5)
	v_mfma_f32_16x16x32_f16 v[48:51], v[12:15], v[246:249], v[48:51]
	s_waitcnt vmcnt(4)
	v_mfma_f32_16x16x32_f16 v[48:51], v[0:3], v[250:253], v[48:51]
	s_waitcnt vmcnt(3)
	v_mfma_f32_16x16x32_f16 v[4:7], v[4:7], v[206:209], 0
	s_waitcnt vmcnt(2)
	v_mfma_f32_16x16x32_f16 v[4:7], v[8:11], v[210:213], v[4:7]
	s_waitcnt vmcnt(1)
	v_mfma_f32_16x16x32_f16 v[4:7], v[12:15], v[214:217], v[4:7]
	s_waitcnt vmcnt(0)
	v_mfma_f32_16x16x32_f16 v[0:3], v[0:3], v[218:221], v[4:7]
	s_nop 7
	ds_write2_b32 v18, v48, v0 offset0:32 offset1:48
	ds_write2_b32 v56, v49, v1 offset0:32 offset1:48
	ds_write2_b32 v57, v50, v2 offset0:32 offset1:48
	ds_write2_b32 v58, v51, v3 offset0:32 offset1:48
	s_waitcnt lgkmcnt(0)
	s_barrier
	s_branch .LBB0_538
